# hyena st1/st2 prologues hand-written (all input loads issued up front; pk-f32 first forward pass)
# speedup vs baseline: 1.1473x; 1.0161x over previous
; HD float2 cmul(float2 a, float2 b){ return make_float2(a.x*b.x - a.y*b.y, a.x*b.y + a.y*b.x); }
; HD void fwd12_padded(float2* Z, const float2* twA, const float2* twB, int t, float2 a0, float2 a1){
;   float2 w1=cmul(twA[t>>6],twB[t&63]), w2=cmul(w1,w1), w3=cmul(w2,w1);
;   Z[t]=make_float2(a0.x+a1.x,a0.y+a1.y);
;   Z[t+4096]=cmul(make_float2(a0.x+a1.y,a0.y-a1.x),w1);
;   Z[t+8192]=cmul(make_float2(a0.x-a1.x,a0.y-a1.y),w2);
;   Z[t+12288]=cmul(make_float2(a0.x-a1.y,a0.y+a1.x),w3);
; }
; __device__ __forceinline__ void phase_hyena(KP kp_, int hf){ asm volatile("" : "+s"(kp_)); const Params p=load_params(kp_);
;     ...
;       } else { int tq=tid; asm volatile("" : "+v"(tq));
;         _Pragma("unroll 4") for (int i=0;i<8;++i){ int t=tq+512*i; fwd12_padded(Z,twA,twB,t,Zs[t],Zs[t+4096]); }
;         __syncthreads();
.LBB0_1319:
	s_mov_b64 s[12:13], -1
	s_and_b64 vcc, exec, s[68:69]
	s_barrier
	s_cbranch_vccz .LBB0_1329
	s_cmp_lg_u32 s89, 1
	s_cbranch_scc0 .LBB0_1324
	v_lshlrev_b32_e32 v15, 3, v86
	v_mov_b32_e32 v0, v15
	v_add_u32_e32 v1, 0x1000, v15
	v_add_u32_e32 v2, 0x2000, v15
	v_add_u32_e32 v4, 0x3000, v15
	v_add_u32_e32 v5, 0x4000, v15
	v_add_u32_e32 v6, 0x5000, v15
	v_add_u32_e32 v7, 0x6000, v15
	v_add_u32_e32 v8, 0x7000, v15
	s_add_u32 s12, s80, 0x8000
	s_addc_u32 s13, s81, 0
	global_load_dwordx2 v[104:105], v0, s[80:81]
	global_load_dwordx2 v[106:107], v0, s[12:13]
	global_load_dwordx2 v[108:109], v1, s[80:81]
	global_load_dwordx2 v[110:111], v1, s[12:13]
	global_load_dwordx2 v[112:113], v2, s[80:81]
	global_load_dwordx2 v[114:115], v2, s[12:13]
	global_load_dwordx2 v[116:117], v4, s[80:81]
	global_load_dwordx2 v[118:119], v4, s[12:13]
	global_load_dwordx2 v[120:121], v5, s[80:81]
	global_load_dwordx2 v[122:123], v5, s[12:13]
	global_load_dwordx2 v[124:125], v6, s[80:81]
	global_load_dwordx2 v[126:127], v6, s[12:13]
	global_load_dwordx2 v[134:135], v7, s[80:81]
	global_load_dwordx2 v[136:137], v7, s[12:13]
	global_load_dwordx2 v[138:139], v8, s[80:81]
	global_load_dwordx2 v[140:141], v8, s[12:13]
	v_lshlrev_b32_e32 v12, 3, v86
	v_add_u32_e32 v13, 0x10000, v12
	v_lshrrev_b32_e32 v14, 6, v86
	v_lshl_add_u32 v14, v14, 3, s88
	v_and_b32_e32 v15, 63, v86
	v_lshl_add_u32 v15, v15, 3, s91
	ds_read_b64 v[10:11], v15
	ds_read_b64 v[58:59], v14 offset:0
	ds_read_b64 v[60:61], v14 offset:64
	ds_read_b64 v[62:63], v14 offset:128
	ds_read_b64 v[64:65], v14 offset:192
	ds_read_b64 v[66:67], v14 offset:256
	ds_read_b64 v[68:69], v14 offset:320
	ds_read_b64 v[70:71], v14 offset:384
	ds_read_b64 v[72:73], v14 offset:448
	s_waitcnt lgkmcnt(0)
	v_pk_mul_f32 v[222:223], v[58:59], v[10:11] op_sel:[1,1] op_sel_hi:[1,0]
	v_pk_fma_f32 v[22:23], v[58:59], v[10:11], v[222:223] op_sel:[0,0,0] op_sel_hi:[0,1,1] neg_lo:[0,0,1]
	v_pk_mul_f32 v[222:223], v[22:23], v[22:23] op_sel:[1,1] op_sel_hi:[1,0]
	v_pk_fma_f32 v[24:25], v[22:23], v[22:23], v[222:223] op_sel:[0,0,0] op_sel_hi:[0,1,1] neg_lo:[0,0,1]
	v_pk_mul_f32 v[222:223], v[24:25], v[22:23] op_sel:[1,1] op_sel_hi:[1,0]
	v_pk_fma_f32 v[26:27], v[24:25], v[22:23], v[222:223] op_sel:[0,0,0] op_sel_hi:[0,1,1] neg_lo:[0,0,1]
	s_waitcnt vmcnt(14)
	v_pk_add_f32 v[84:85], v[104:105], v[106:107]
	ds_write_b64 v12, v[84:85] offset:0
	v_pk_add_f32 v[74:75], v[104:105], v[106:107] op_sel:[0,1] op_sel_hi:[1,0] neg_hi:[0,1]
	v_pk_mul_f32 v[222:223], v[74:75], v[22:23] op_sel:[1,1] op_sel_hi:[1,0]
	v_pk_fma_f32 v[84:85], v[74:75], v[22:23], v[222:223] op_sel:[0,0,0] op_sel_hi:[0,1,1] neg_lo:[0,0,1]
	ds_write_b64 v12, v[84:85] offset:32768
	v_pk_add_f32 v[74:75], v[104:105], v[106:107] neg_lo:[0,1] neg_hi:[0,1]
	v_pk_mul_f32 v[222:223], v[74:75], v[24:25] op_sel:[1,1] op_sel_hi:[1,0]
	v_pk_fma_f32 v[84:85], v[74:75], v[24:25], v[222:223] op_sel:[0,0,0] op_sel_hi:[0,1,1] neg_lo:[0,0,1]
	ds_write_b64 v13, v[84:85] offset:0
	v_pk_add_f32 v[74:75], v[104:105], v[106:107] op_sel:[0,1] op_sel_hi:[1,0] neg_lo:[0,1]
	v_pk_mul_f32 v[222:223], v[74:75], v[26:27] op_sel:[1,1] op_sel_hi:[1,0]
	v_pk_fma_f32 v[84:85], v[74:75], v[26:27], v[222:223] op_sel:[0,0,0] op_sel_hi:[0,1,1] neg_lo:[0,0,1]
	ds_write_b64 v13, v[84:85] offset:32768
	v_pk_mul_f32 v[222:223], v[60:61], v[10:11] op_sel:[1,1] op_sel_hi:[1,0]
	v_pk_fma_f32 v[22:23], v[60:61], v[10:11], v[222:223] op_sel:[0,0,0] op_sel_hi:[0,1,1] neg_lo:[0,0,1]
	v_pk_mul_f32 v[222:223], v[22:23], v[22:23] op_sel:[1,1] op_sel_hi:[1,0]
	v_pk_fma_f32 v[24:25], v[22:23], v[22:23], v[222:223] op_sel:[0,0,0] op_sel_hi:[0,1,1] neg_lo:[0,0,1]
	v_pk_mul_f32 v[222:223], v[24:25], v[22:23] op_sel:[1,1] op_sel_hi:[1,0]
	v_pk_fma_f32 v[26:27], v[24:25], v[22:23], v[222:223] op_sel:[0,0,0] op_sel_hi:[0,1,1] neg_lo:[0,0,1]
	s_waitcnt vmcnt(12)
	v_pk_add_f32 v[84:85], v[108:109], v[110:111]
	ds_write_b64 v12, v[84:85] offset:4096
	v_pk_add_f32 v[74:75], v[108:109], v[110:111] op_sel:[0,1] op_sel_hi:[1,0] neg_hi:[0,1]
	v_pk_mul_f32 v[222:223], v[74:75], v[22:23] op_sel:[1,1] op_sel_hi:[1,0]
	v_pk_fma_f32 v[84:85], v[74:75], v[22:23], v[222:223] op_sel:[0,0,0] op_sel_hi:[0,1,1] neg_lo:[0,0,1]
	ds_write_b64 v12, v[84:85] offset:36864
	v_pk_add_f32 v[74:75], v[108:109], v[110:111] neg_lo:[0,1] neg_hi:[0,1]
	v_pk_mul_f32 v[222:223], v[74:75], v[24:25] op_sel:[1,1] op_sel_hi:[1,0]
	v_pk_fma_f32 v[84:85], v[74:75], v[24:25], v[222:223] op_sel:[0,0,0] op_sel_hi:[0,1,1] neg_lo:[0,0,1]
	ds_write_b64 v13, v[84:85] offset:4096
	v_pk_add_f32 v[74:75], v[108:109], v[110:111] op_sel:[0,1] op_sel_hi:[1,0] neg_lo:[0,1]
	v_pk_mul_f32 v[222:223], v[74:75], v[26:27] op_sel:[1,1] op_sel_hi:[1,0]
	v_pk_fma_f32 v[84:85], v[74:75], v[26:27], v[222:223] op_sel:[0,0,0] op_sel_hi:[0,1,1] neg_lo:[0,0,1]
	ds_write_b64 v13, v[84:85] offset:36864
	v_pk_mul_f32 v[222:223], v[62:63], v[10:11] op_sel:[1,1] op_sel_hi:[1,0]
	v_pk_fma_f32 v[22:23], v[62:63], v[10:11], v[222:223] op_sel:[0,0,0] op_sel_hi:[0,1,1] neg_lo:[0,0,1]
	v_pk_mul_f32 v[222:223], v[22:23], v[22:23] op_sel:[1,1] op_sel_hi:[1,0]
	v_pk_fma_f32 v[24:25], v[22:23], v[22:23], v[222:223] op_sel:[0,0,0] op_sel_hi:[0,1,1] neg_lo:[0,0,1]
	v_pk_mul_f32 v[222:223], v[24:25], v[22:23] op_sel:[1,1] op_sel_hi:[1,0]
	v_pk_fma_f32 v[26:27], v[24:25], v[22:23], v[222:223] op_sel:[0,0,0] op_sel_hi:[0,1,1] neg_lo:[0,0,1]
	s_waitcnt vmcnt(10)
; HD float2 cmul(float2 a, float2 b){ return make_float2(a.x*b.x - a.y*b.y, a.x*b.y + a.y*b.x); }
; HD void fwd12_padded(float2* Z, const float2* twA, const float2* twB, int t, float2 a0, float2 a1){
;   float2 w1=cmul(twA[t>>6],twB[t&63]), w2=cmul(w1,w1), w3=cmul(w2,w1);
;   Z[t]=make_float2(a0.x+a1.x,a0.y+a1.y);
;   Z[t+4096]=cmul(make_float2(a0.x+a1.y,a0.y-a1.x),w1);
;   Z[t+8192]=cmul(make_float2(a0.x-a1.x,a0.y-a1.y),w2);
;   Z[t+12288]=cmul(make_float2(a0.x-a1.y,a0.y+a1.x),w3);
; }
; __device__ __forceinline__ void phase_hyena(KP kp_, int hf){ asm volatile("" : "+s"(kp_)); const Params p=load_params(kp_);
;     ...
;         _Pragma("unroll 4") for (int i=0;i<8;++i){ int t=tq+512*i; fwd12_padded(Z,twA,twB,t,Zs[t],Zs[t+4096]); }
	v_pk_add_f32 v[84:85], v[112:113], v[114:115]
	ds_write_b64 v12, v[84:85] offset:8192
	v_pk_add_f32 v[74:75], v[112:113], v[114:115] op_sel:[0,1] op_sel_hi:[1,0] neg_hi:[0,1]
	v_pk_mul_f32 v[222:223], v[74:75], v[22:23] op_sel:[1,1] op_sel_hi:[1,0]
	v_pk_fma_f32 v[84:85], v[74:75], v[22:23], v[222:223] op_sel:[0,0,0] op_sel_hi:[0,1,1] neg_lo:[0,0,1]
	ds_write_b64 v12, v[84:85] offset:40960
	v_pk_add_f32 v[74:75], v[112:113], v[114:115] neg_lo:[0,1] neg_hi:[0,1]
	v_pk_mul_f32 v[222:223], v[74:75], v[24:25] op_sel:[1,1] op_sel_hi:[1,0]
	v_pk_fma_f32 v[84:85], v[74:75], v[24:25], v[222:223] op_sel:[0,0,0] op_sel_hi:[0,1,1] neg_lo:[0,0,1]
	ds_write_b64 v13, v[84:85] offset:8192
	v_pk_add_f32 v[74:75], v[112:113], v[114:115] op_sel:[0,1] op_sel_hi:[1,0] neg_lo:[0,1]
	v_pk_mul_f32 v[222:223], v[74:75], v[26:27] op_sel:[1,1] op_sel_hi:[1,0]
	v_pk_fma_f32 v[84:85], v[74:75], v[26:27], v[222:223] op_sel:[0,0,0] op_sel_hi:[0,1,1] neg_lo:[0,0,1]
	ds_write_b64 v13, v[84:85] offset:40960
	v_pk_mul_f32 v[222:223], v[64:65], v[10:11] op_sel:[1,1] op_sel_hi:[1,0]
	v_pk_fma_f32 v[22:23], v[64:65], v[10:11], v[222:223] op_sel:[0,0,0] op_sel_hi:[0,1,1] neg_lo:[0,0,1]
	v_pk_mul_f32 v[222:223], v[22:23], v[22:23] op_sel:[1,1] op_sel_hi:[1,0]
	v_pk_fma_f32 v[24:25], v[22:23], v[22:23], v[222:223] op_sel:[0,0,0] op_sel_hi:[0,1,1] neg_lo:[0,0,1]
	v_pk_mul_f32 v[222:223], v[24:25], v[22:23] op_sel:[1,1] op_sel_hi:[1,0]
	v_pk_fma_f32 v[26:27], v[24:25], v[22:23], v[222:223] op_sel:[0,0,0] op_sel_hi:[0,1,1] neg_lo:[0,0,1]
	s_waitcnt vmcnt(8)
	v_pk_add_f32 v[84:85], v[116:117], v[118:119]
	ds_write_b64 v12, v[84:85] offset:12288
	v_pk_add_f32 v[74:75], v[116:117], v[118:119] op_sel:[0,1] op_sel_hi:[1,0] neg_hi:[0,1]
	v_pk_mul_f32 v[222:223], v[74:75], v[22:23] op_sel:[1,1] op_sel_hi:[1,0]
	v_pk_fma_f32 v[84:85], v[74:75], v[22:23], v[222:223] op_sel:[0,0,0] op_sel_hi:[0,1,1] neg_lo:[0,0,1]
	ds_write_b64 v12, v[84:85] offset:45056
	v_pk_add_f32 v[74:75], v[116:117], v[118:119] neg_lo:[0,1] neg_hi:[0,1]
	v_pk_mul_f32 v[222:223], v[74:75], v[24:25] op_sel:[1,1] op_sel_hi:[1,0]
	v_pk_fma_f32 v[84:85], v[74:75], v[24:25], v[222:223] op_sel:[0,0,0] op_sel_hi:[0,1,1] neg_lo:[0,0,1]
	ds_write_b64 v13, v[84:85] offset:12288
	v_pk_add_f32 v[74:75], v[116:117], v[118:119] op_sel:[0,1] op_sel_hi:[1,0] neg_lo:[0,1]
	v_pk_mul_f32 v[222:223], v[74:75], v[26:27] op_sel:[1,1] op_sel_hi:[1,0]
	v_pk_fma_f32 v[84:85], v[74:75], v[26:27], v[222:223] op_sel:[0,0,0] op_sel_hi:[0,1,1] neg_lo:[0,0,1]
	ds_write_b64 v13, v[84:85] offset:45056
	v_pk_mul_f32 v[222:223], v[66:67], v[10:11] op_sel:[1,1] op_sel_hi:[1,0]
	v_pk_fma_f32 v[22:23], v[66:67], v[10:11], v[222:223] op_sel:[0,0,0] op_sel_hi:[0,1,1] neg_lo:[0,0,1]
	v_pk_mul_f32 v[222:223], v[22:23], v[22:23] op_sel:[1,1] op_sel_hi:[1,0]
	v_pk_fma_f32 v[24:25], v[22:23], v[22:23], v[222:223] op_sel:[0,0,0] op_sel_hi:[0,1,1] neg_lo:[0,0,1]
	v_pk_mul_f32 v[222:223], v[24:25], v[22:23] op_sel:[1,1] op_sel_hi:[1,0]
	v_pk_fma_f32 v[26:27], v[24:25], v[22:23], v[222:223] op_sel:[0,0,0] op_sel_hi:[0,1,1] neg_lo:[0,0,1]
	s_waitcnt vmcnt(6)
	v_pk_add_f32 v[84:85], v[120:121], v[122:123]
	ds_write_b64 v12, v[84:85] offset:16384
	v_pk_add_f32 v[74:75], v[120:121], v[122:123] op_sel:[0,1] op_sel_hi:[1,0] neg_hi:[0,1]
	v_pk_mul_f32 v[222:223], v[74:75], v[22:23] op_sel:[1,1] op_sel_hi:[1,0]
	v_pk_fma_f32 v[84:85], v[74:75], v[22:23], v[222:223] op_sel:[0,0,0] op_sel_hi:[0,1,1] neg_lo:[0,0,1]
	ds_write_b64 v12, v[84:85] offset:49152
	v_pk_add_f32 v[74:75], v[120:121], v[122:123] neg_lo:[0,1] neg_hi:[0,1]
	v_pk_mul_f32 v[222:223], v[74:75], v[24:25] op_sel:[1,1] op_sel_hi:[1,0]
	v_pk_fma_f32 v[84:85], v[74:75], v[24:25], v[222:223] op_sel:[0,0,0] op_sel_hi:[0,1,1] neg_lo:[0,0,1]
	ds_write_b64 v13, v[84:85] offset:16384
	v_pk_add_f32 v[74:75], v[120:121], v[122:123] op_sel:[0,1] op_sel_hi:[1,0] neg_lo:[0,1]
	v_pk_mul_f32 v[222:223], v[74:75], v[26:27] op_sel:[1,1] op_sel_hi:[1,0]
	v_pk_fma_f32 v[84:85], v[74:75], v[26:27], v[222:223] op_sel:[0,0,0] op_sel_hi:[0,1,1] neg_lo:[0,0,1]
	ds_write_b64 v13, v[84:85] offset:49152
	v_pk_mul_f32 v[222:223], v[68:69], v[10:11] op_sel:[1,1] op_sel_hi:[1,0]
	v_pk_fma_f32 v[22:23], v[68:69], v[10:11], v[222:223] op_sel:[0,0,0] op_sel_hi:[0,1,1] neg_lo:[0,0,1]
	v_pk_mul_f32 v[222:223], v[22:23], v[22:23] op_sel:[1,1] op_sel_hi:[1,0]
	v_pk_fma_f32 v[24:25], v[22:23], v[22:23], v[222:223] op_sel:[0,0,0] op_sel_hi:[0,1,1] neg_lo:[0,0,1]
	v_pk_mul_f32 v[222:223], v[24:25], v[22:23] op_sel:[1,1] op_sel_hi:[1,0]
	v_pk_fma_f32 v[26:27], v[24:25], v[22:23], v[222:223] op_sel:[0,0,0] op_sel_hi:[0,1,1] neg_lo:[0,0,1]
	s_waitcnt vmcnt(4)
	v_pk_add_f32 v[84:85], v[124:125], v[126:127]
	ds_write_b64 v12, v[84:85] offset:20480
	v_pk_add_f32 v[74:75], v[124:125], v[126:127] op_sel:[0,1] op_sel_hi:[1,0] neg_hi:[0,1]
	v_pk_mul_f32 v[222:223], v[74:75], v[22:23] op_sel:[1,1] op_sel_hi:[1,0]
	v_pk_fma_f32 v[84:85], v[74:75], v[22:23], v[222:223] op_sel:[0,0,0] op_sel_hi:[0,1,1] neg_lo:[0,0,1]
	ds_write_b64 v12, v[84:85] offset:53248
	v_pk_add_f32 v[74:75], v[124:125], v[126:127] neg_lo:[0,1] neg_hi:[0,1]
	v_pk_mul_f32 v[222:223], v[74:75], v[24:25] op_sel:[1,1] op_sel_hi:[1,0]
	v_pk_fma_f32 v[84:85], v[74:75], v[24:25], v[222:223] op_sel:[0,0,0] op_sel_hi:[0,1,1] neg_lo:[0,0,1]
	ds_write_b64 v13, v[84:85] offset:20480
	v_pk_add_f32 v[74:75], v[124:125], v[126:127] op_sel:[0,1] op_sel_hi:[1,0] neg_lo:[0,1]
	v_pk_mul_f32 v[222:223], v[74:75], v[26:27] op_sel:[1,1] op_sel_hi:[1,0]
	v_pk_fma_f32 v[84:85], v[74:75], v[26:27], v[222:223] op_sel:[0,0,0] op_sel_hi:[0,1,1] neg_lo:[0,0,1]
	ds_write_b64 v13, v[84:85] offset:53248
	v_pk_mul_f32 v[222:223], v[70:71], v[10:11] op_sel:[1,1] op_sel_hi:[1,0]
	v_pk_fma_f32 v[22:23], v[70:71], v[10:11], v[222:223] op_sel:[0,0,0] op_sel_hi:[0,1,1] neg_lo:[0,0,1]
	v_pk_mul_f32 v[222:223], v[22:23], v[22:23] op_sel:[1,1] op_sel_hi:[1,0]
	v_pk_fma_f32 v[24:25], v[22:23], v[22:23], v[222:223] op_sel:[0,0,0] op_sel_hi:[0,1,1] neg_lo:[0,0,1]
	v_pk_mul_f32 v[222:223], v[24:25], v[22:23] op_sel:[1,1] op_sel_hi:[1,0]
	v_pk_fma_f32 v[26:27], v[24:25], v[22:23], v[222:223] op_sel:[0,0,0] op_sel_hi:[0,1,1] neg_lo:[0,0,1]
	s_waitcnt vmcnt(2)
; HD float2 cmul(float2 a, float2 b){ return make_float2(a.x*b.x - a.y*b.y, a.x*b.y + a.y*b.x); }
; HD void fwd12_padded(float2* Z, const float2* twA, const float2* twB, int t, float2 a0, float2 a1){
;   float2 w1=cmul(twA[t>>6],twB[t&63]), w2=cmul(w1,w1), w3=cmul(w2,w1);
;   Z[t]=make_float2(a0.x+a1.x,a0.y+a1.y);
;   Z[t+4096]=cmul(make_float2(a0.x+a1.y,a0.y-a1.x),w1);
;   Z[t+8192]=cmul(make_float2(a0.x-a1.x,a0.y-a1.y),w2);
;   Z[t+12288]=cmul(make_float2(a0.x-a1.y,a0.y+a1.x),w3);
; }
; __device__ __forceinline__ void phase_hyena(KP kp_, int hf){ asm volatile("" : "+s"(kp_)); const Params p=load_params(kp_);
;     ...
;       else if (st==1){ int tq=tid; asm volatile("" : "+v"(tq));
;         _Pragma("unroll 4") for (int i=0;i<8;++i){ int t=tq+512*i;
;           float2 a0=make_float2(hconv3(rv,t,wv0,wv1,wv2,bv_), hconv3(rv+8192,t,wv0,wv1,wv2,bv_));
;           float2 a1=make_float2(hconv3(rv,t+4096,wv0,wv1,wv2,bv_), hconv3(rv+8192,t+4096,wv0,wv1,wv2,bv_));
;           fwd12_padded(Z,twA,twB,t,a0,a1); }
;         __syncthreads();
;       } else { int tq=tid; asm volatile("" : "+v"(tq));
;         _Pragma("unroll 4") for (int i=0;i<8;++i){ int t=tq+512*i; fwd12_padded(Z,twA,twB,t,Zs[t],Zs[t+4096]); }
;         __syncthreads();
	v_pk_add_f32 v[84:85], v[134:135], v[136:137]
	ds_write_b64 v12, v[84:85] offset:24576
	v_pk_add_f32 v[74:75], v[134:135], v[136:137] op_sel:[0,1] op_sel_hi:[1,0] neg_hi:[0,1]
	v_pk_mul_f32 v[222:223], v[74:75], v[22:23] op_sel:[1,1] op_sel_hi:[1,0]
	v_pk_fma_f32 v[84:85], v[74:75], v[22:23], v[222:223] op_sel:[0,0,0] op_sel_hi:[0,1,1] neg_lo:[0,0,1]
	ds_write_b64 v12, v[84:85] offset:57344
	v_pk_add_f32 v[74:75], v[134:135], v[136:137] neg_lo:[0,1] neg_hi:[0,1]
	v_pk_mul_f32 v[222:223], v[74:75], v[24:25] op_sel:[1,1] op_sel_hi:[1,0]
	v_pk_fma_f32 v[84:85], v[74:75], v[24:25], v[222:223] op_sel:[0,0,0] op_sel_hi:[0,1,1] neg_lo:[0,0,1]
	ds_write_b64 v13, v[84:85] offset:24576
	v_pk_add_f32 v[74:75], v[134:135], v[136:137] op_sel:[0,1] op_sel_hi:[1,0] neg_lo:[0,1]
	v_pk_mul_f32 v[222:223], v[74:75], v[26:27] op_sel:[1,1] op_sel_hi:[1,0]
	v_pk_fma_f32 v[84:85], v[74:75], v[26:27], v[222:223] op_sel:[0,0,0] op_sel_hi:[0,1,1] neg_lo:[0,0,1]
	ds_write_b64 v13, v[84:85] offset:57344
	v_pk_mul_f32 v[222:223], v[72:73], v[10:11] op_sel:[1,1] op_sel_hi:[1,0]
	v_pk_fma_f32 v[22:23], v[72:73], v[10:11], v[222:223] op_sel:[0,0,0] op_sel_hi:[0,1,1] neg_lo:[0,0,1]
	v_pk_mul_f32 v[222:223], v[22:23], v[22:23] op_sel:[1,1] op_sel_hi:[1,0]
	v_pk_fma_f32 v[24:25], v[22:23], v[22:23], v[222:223] op_sel:[0,0,0] op_sel_hi:[0,1,1] neg_lo:[0,0,1]
	v_pk_mul_f32 v[222:223], v[24:25], v[22:23] op_sel:[1,1] op_sel_hi:[1,0]
	v_pk_fma_f32 v[26:27], v[24:25], v[22:23], v[222:223] op_sel:[0,0,0] op_sel_hi:[0,1,1] neg_lo:[0,0,1]
	s_waitcnt vmcnt(0)
	v_pk_add_f32 v[84:85], v[138:139], v[140:141]
	ds_write_b64 v12, v[84:85] offset:28672
	v_pk_add_f32 v[74:75], v[138:139], v[140:141] op_sel:[0,1] op_sel_hi:[1,0] neg_hi:[0,1]
	v_pk_mul_f32 v[222:223], v[74:75], v[22:23] op_sel:[1,1] op_sel_hi:[1,0]
	v_pk_fma_f32 v[84:85], v[74:75], v[22:23], v[222:223] op_sel:[0,0,0] op_sel_hi:[0,1,1] neg_lo:[0,0,1]
	ds_write_b64 v12, v[84:85] offset:61440
	v_pk_add_f32 v[74:75], v[138:139], v[140:141] neg_lo:[0,1] neg_hi:[0,1]
	v_pk_mul_f32 v[222:223], v[74:75], v[24:25] op_sel:[1,1] op_sel_hi:[1,0]
	v_pk_fma_f32 v[84:85], v[74:75], v[24:25], v[222:223] op_sel:[0,0,0] op_sel_hi:[0,1,1] neg_lo:[0,0,1]
	ds_write_b64 v13, v[84:85] offset:28672
	v_pk_add_f32 v[74:75], v[138:139], v[140:141] op_sel:[0,1] op_sel_hi:[1,0] neg_lo:[0,1]
	v_pk_mul_f32 v[222:223], v[74:75], v[26:27] op_sel:[1,1] op_sel_hi:[1,0]
	v_pk_fma_f32 v[84:85], v[74:75], v[26:27], v[222:223] op_sel:[0,0,0] op_sel_hi:[0,1,1] neg_lo:[0,0,1]
	ds_write_b64 v13, v[84:85] offset:61440
	s_mov_b32 s12, 0x8000
	s_mov_b64 s[12:13], 0
	s_waitcnt lgkmcnt(0)
	s_barrier
.LBB0_1324:
	s_and_b64 vcc, exec, s[12:13]
	s_cbranch_vccz .LBB0_1328
	v_lshlrev_b32_e32 v15, 1, v86
	v_add_u32_e32 v0, 0x0, v15
	v_add_u32_e32 v1, 0x4000, v15
	v_add_u32_e32 v2, 0x2000, v15
	v_add_u32_e32 v4, 0x6000, v15
	v_add_u32_e32 v5, 0x1000, v15
	v_add_u32_e32 v6, 0x5000, v15
	v_add_u32_e32 v7, 0x3000, v15
	v_add_u32_e32 v8, 0x7000, v15
	s_sub_u32 s12, s96, 0x2000000
	s_subb_u32 s13, s97, 0
	global_load_ushort v104, v0, s[12:13] offset:0
	global_load_ushort v105, v1, s[12:13] offset:0
	global_load_ushort v106, v2, s[12:13] offset:0
	global_load_ushort v107, v4, s[12:13] offset:0
	global_load_ushort v108, v0, s[12:13] offset:1024
	global_load_ushort v109, v1, s[12:13] offset:1024
	global_load_ushort v110, v2, s[12:13] offset:1024
	global_load_ushort v111, v4, s[12:13] offset:1024
	global_load_ushort v112, v0, s[12:13] offset:2048
	global_load_ushort v113, v1, s[12:13] offset:2048
	global_load_ushort v114, v2, s[12:13] offset:2048
	global_load_ushort v115, v4, s[12:13] offset:2048
	global_load_ushort v116, v0, s[12:13] offset:3072
	global_load_ushort v117, v1, s[12:13] offset:3072
	global_load_ushort v118, v2, s[12:13] offset:3072
	global_load_ushort v119, v4, s[12:13] offset:3072
	global_load_ushort v120, v5, s[12:13] offset:0
	global_load_ushort v121, v6, s[12:13] offset:0
	global_load_ushort v122, v7, s[12:13] offset:0
	global_load_ushort v123, v8, s[12:13] offset:0
	global_load_ushort v124, v5, s[12:13] offset:1024
	global_load_ushort v125, v6, s[12:13] offset:1024
	global_load_ushort v126, v7, s[12:13] offset:1024
	global_load_ushort v127, v8, s[12:13] offset:1024
	global_load_ushort v134, v5, s[12:13] offset:2048
	global_load_ushort v135, v6, s[12:13] offset:2048
	global_load_ushort v136, v7, s[12:13] offset:2048
	global_load_ushort v137, v8, s[12:13] offset:2048
	global_load_ushort v138, v5, s[12:13] offset:3072
	global_load_ushort v139, v6, s[12:13] offset:3072
	global_load_ushort v140, v7, s[12:13] offset:3072
	global_load_ushort v141, v8, s[12:13] offset:3072
	v_lshlrev_b32_e32 v12, 3, v86
	v_add_u32_e32 v13, 0x10000, v12
	v_lshrrev_b32_e32 v14, 6, v86
	v_lshl_add_u32 v14, v14, 3, s88
	v_and_b32_e32 v15, 63, v86
	v_lshl_add_u32 v15, v15, 3, s91
	ds_read_b64 v[10:11], v15
	ds_read_b64 v[58:59], v14 offset:0
	ds_read_b64 v[60:61], v14 offset:64
	ds_read_b64 v[62:63], v14 offset:128
	ds_read_b64 v[64:65], v14 offset:192
	ds_read_b64 v[66:67], v14 offset:256
	ds_read_b64 v[68:69], v14 offset:320
	ds_read_b64 v[70:71], v14 offset:384
	ds_read_b64 v[72:73], v14 offset:448
	s_waitcnt lgkmcnt(0)
	v_pk_mul_f32 v[222:223], v[58:59], v[10:11] op_sel:[1,1] op_sel_hi:[1,0]
	v_pk_fma_f32 v[22:23], v[58:59], v[10:11], v[222:223] op_sel:[0,0,0] op_sel_hi:[0,1,1] neg_lo:[0,0,1]
	v_pk_mul_f32 v[222:223], v[22:23], v[22:23] op_sel:[1,1] op_sel_hi:[1,0]
	v_pk_fma_f32 v[24:25], v[22:23], v[22:23], v[222:223] op_sel:[0,0,0] op_sel_hi:[0,1,1] neg_lo:[0,0,1]
	v_pk_mul_f32 v[222:223], v[24:25], v[22:23] op_sel:[1,1] op_sel_hi:[1,0]
	v_pk_fma_f32 v[26:27], v[24:25], v[22:23], v[222:223] op_sel:[0,0,0] op_sel_hi:[0,1,1] neg_lo:[0,0,1]
	s_waitcnt vmcnt(28)
; __device__ __forceinline__ float bf2f(u16 h){ return __uint_as_float(((unsigned)h)<<16); }
; __device__ __forceinline__ float hconv3(const u16* __restrict__ row, int t, float w0, float w1, float w2, float bias){
;   float m = bf2f(row[t]);
;   int mi=__float_as_int(m);
;   float l=__int_as_float(__builtin_amdgcn_update_dpp(0, mi, 0x138, 0xf, 0xf, false));
;   float r=__int_as_float(__builtin_amdgcn_update_dpp(0, mi, 0x130, 0xf, 0xf, false));
;   return w0*l+w1*m+w2*r+bias;
; }
; __device__ __forceinline__ void phase_hyena(KP kp_, int hf){ asm volatile("" : "+s"(kp_)); const Params p=load_params(kp_);
;     ...
;       else if (st==1){ int tq=tid; asm volatile("" : "+v"(tq));
;         _Pragma("unroll 4") for (int i=0;i<8;++i){ int t=tq+512*i;
;           float2 a0=make_float2(hconv3(rv,t,wv0,wv1,wv2,bv_), hconv3(rv+8192,t,wv0,wv1,wv2,bv_));
;           float2 a1=make_float2(hconv3(rv,t+4096,wv0,wv1,wv2,bv_), hconv3(rv+8192,t+4096,wv0,wv1,wv2,bv_));
;           fwd12_padded(Z,twA,twB,t,a0,a1); }
	v_lshlrev_b32_e32 v224, 16, v104
	v_lshlrev_b32_e32 v225, 16, v105
	v_mov_b32_e32 v226, 0
	v_mov_b32_e32 v227, 0
	v_mov_b32_e32 v80, 0
	v_mov_b32_e32 v81, 0
	v_mov_b32_dpp v226, v224 wave_shr:1 row_mask:0xf bank_mask:0xf
	v_mov_b32_dpp v227, v225 wave_shr:1 row_mask:0xf bank_mask:0xf
	v_mov_b32_dpp v80, v224 wave_shl:1 row_mask:0xf bank_mask:0xf
	v_mov_b32_dpp v81, v225 wave_shl:1 row_mask:0xf bank_mask:0xf
	v_pk_mul_f32 v[82:83], v[34:35], v[224:225]
	v_pk_fma_f32 v[82:83], v[32:33], v[226:227], v[82:83]
	v_pk_fma_f32 v[82:83], v[36:37], v[80:81], v[82:83]
	v_pk_add_f32 v[28:29], v[38:39], v[82:83]
	v_lshlrev_b32_e32 v224, 16, v106
	v_lshlrev_b32_e32 v225, 16, v107
	v_mov_b32_e32 v226, 0
	v_mov_b32_e32 v227, 0
	v_mov_b32_e32 v80, 0
	v_mov_b32_e32 v81, 0
	v_mov_b32_dpp v226, v224 wave_shr:1 row_mask:0xf bank_mask:0xf
	v_mov_b32_dpp v227, v225 wave_shr:1 row_mask:0xf bank_mask:0xf
	v_mov_b32_dpp v80, v224 wave_shl:1 row_mask:0xf bank_mask:0xf
	v_mov_b32_dpp v81, v225 wave_shl:1 row_mask:0xf bank_mask:0xf
	v_pk_mul_f32 v[82:83], v[34:35], v[224:225]
	v_pk_fma_f32 v[82:83], v[32:33], v[226:227], v[82:83]
	v_pk_fma_f32 v[82:83], v[36:37], v[80:81], v[82:83]
	v_pk_add_f32 v[30:31], v[38:39], v[82:83]
	v_pk_add_f32 v[84:85], v[28:29], v[30:31]
	ds_write_b64 v12, v[84:85] offset:0
	v_pk_add_f32 v[74:75], v[28:29], v[30:31] op_sel:[0,1] op_sel_hi:[1,0] neg_hi:[0,1]
	v_pk_mul_f32 v[222:223], v[74:75], v[22:23] op_sel:[1,1] op_sel_hi:[1,0]
	v_pk_fma_f32 v[84:85], v[74:75], v[22:23], v[222:223] op_sel:[0,0,0] op_sel_hi:[0,1,1] neg_lo:[0,0,1]
	ds_write_b64 v12, v[84:85] offset:32768
	v_pk_add_f32 v[74:75], v[28:29], v[30:31] neg_lo:[0,1] neg_hi:[0,1]
	v_pk_mul_f32 v[222:223], v[74:75], v[24:25] op_sel:[1,1] op_sel_hi:[1,0]
	v_pk_fma_f32 v[84:85], v[74:75], v[24:25], v[222:223] op_sel:[0,0,0] op_sel_hi:[0,1,1] neg_lo:[0,0,1]
	ds_write_b64 v13, v[84:85] offset:0
	v_pk_add_f32 v[74:75], v[28:29], v[30:31] op_sel:[0,1] op_sel_hi:[1,0] neg_lo:[0,1]
	v_pk_mul_f32 v[222:223], v[74:75], v[26:27] op_sel:[1,1] op_sel_hi:[1,0]
	v_pk_fma_f32 v[84:85], v[74:75], v[26:27], v[222:223] op_sel:[0,0,0] op_sel_hi:[0,1,1] neg_lo:[0,0,1]
	ds_write_b64 v13, v[84:85] offset:32768
	v_pk_mul_f32 v[222:223], v[60:61], v[10:11] op_sel:[1,1] op_sel_hi:[1,0]
	v_pk_fma_f32 v[22:23], v[60:61], v[10:11], v[222:223] op_sel:[0,0,0] op_sel_hi:[0,1,1] neg_lo:[0,0,1]
	v_pk_mul_f32 v[222:223], v[22:23], v[22:23] op_sel:[1,1] op_sel_hi:[1,0]
	v_pk_fma_f32 v[24:25], v[22:23], v[22:23], v[222:223] op_sel:[0,0,0] op_sel_hi:[0,1,1] neg_lo:[0,0,1]
	v_pk_mul_f32 v[222:223], v[24:25], v[22:23] op_sel:[1,1] op_sel_hi:[1,0]
	v_pk_fma_f32 v[26:27], v[24:25], v[22:23], v[222:223] op_sel:[0,0,0] op_sel_hi:[0,1,1] neg_lo:[0,0,1]
	s_waitcnt vmcnt(24)
	v_lshlrev_b32_e32 v224, 16, v108
	v_lshlrev_b32_e32 v225, 16, v109
	v_mov_b32_e32 v226, 0
	v_mov_b32_e32 v227, 0
	v_mov_b32_e32 v80, 0
	v_mov_b32_e32 v81, 0
	v_mov_b32_dpp v226, v224 wave_shr:1 row_mask:0xf bank_mask:0xf
	v_mov_b32_dpp v227, v225 wave_shr:1 row_mask:0xf bank_mask:0xf
	v_mov_b32_dpp v80, v224 wave_shl:1 row_mask:0xf bank_mask:0xf
	v_mov_b32_dpp v81, v225 wave_shl:1 row_mask:0xf bank_mask:0xf
	v_pk_mul_f32 v[82:83], v[34:35], v[224:225]
	v_pk_fma_f32 v[82:83], v[32:33], v[226:227], v[82:83]
	v_pk_fma_f32 v[82:83], v[36:37], v[80:81], v[82:83]
	v_pk_add_f32 v[28:29], v[38:39], v[82:83]
	v_lshlrev_b32_e32 v224, 16, v110
	v_lshlrev_b32_e32 v225, 16, v111
	v_mov_b32_e32 v226, 0
	v_mov_b32_e32 v227, 0
	v_mov_b32_e32 v80, 0
	v_mov_b32_e32 v81, 0
	v_mov_b32_dpp v226, v224 wave_shr:1 row_mask:0xf bank_mask:0xf
	v_mov_b32_dpp v227, v225 wave_shr:1 row_mask:0xf bank_mask:0xf
	v_mov_b32_dpp v80, v224 wave_shl:1 row_mask:0xf bank_mask:0xf
	v_mov_b32_dpp v81, v225 wave_shl:1 row_mask:0xf bank_mask:0xf
	v_pk_mul_f32 v[82:83], v[34:35], v[224:225]
	v_pk_fma_f32 v[82:83], v[32:33], v[226:227], v[82:83]
	v_pk_fma_f32 v[82:83], v[36:37], v[80:81], v[82:83]
	v_pk_add_f32 v[30:31], v[38:39], v[82:83]
	v_pk_add_f32 v[84:85], v[28:29], v[30:31]
	ds_write_b64 v12, v[84:85] offset:4096
	v_pk_add_f32 v[74:75], v[28:29], v[30:31] op_sel:[0,1] op_sel_hi:[1,0] neg_hi:[0,1]
	v_pk_mul_f32 v[222:223], v[74:75], v[22:23] op_sel:[1,1] op_sel_hi:[1,0]
	v_pk_fma_f32 v[84:85], v[74:75], v[22:23], v[222:223] op_sel:[0,0,0] op_sel_hi:[0,1,1] neg_lo:[0,0,1]
	ds_write_b64 v12, v[84:85] offset:36864
	v_pk_add_f32 v[74:75], v[28:29], v[30:31] neg_lo:[0,1] neg_hi:[0,1]
	v_pk_mul_f32 v[222:223], v[74:75], v[24:25] op_sel:[1,1] op_sel_hi:[1,0]
	v_pk_fma_f32 v[84:85], v[74:75], v[24:25], v[222:223] op_sel:[0,0,0] op_sel_hi:[0,1,1] neg_lo:[0,0,1]
	ds_write_b64 v13, v[84:85] offset:4096
	v_pk_add_f32 v[74:75], v[28:29], v[30:31] op_sel:[0,1] op_sel_hi:[1,0] neg_lo:[0,1]
	v_pk_mul_f32 v[222:223], v[74:75], v[26:27] op_sel:[1,1] op_sel_hi:[1,0]
	v_pk_fma_f32 v[84:85], v[74:75], v[26:27], v[222:223] op_sel:[0,0,0] op_sel_hi:[0,1,1] neg_lo:[0,0,1]
	ds_write_b64 v13, v[84:85] offset:36864
	v_pk_mul_f32 v[222:223], v[62:63], v[10:11] op_sel:[1,1] op_sel_hi:[1,0]
	v_pk_fma_f32 v[22:23], v[62:63], v[10:11], v[222:223] op_sel:[0,0,0] op_sel_hi:[0,1,1] neg_lo:[0,0,1]
	v_pk_mul_f32 v[222:223], v[22:23], v[22:23] op_sel:[1,1] op_sel_hi:[1,0]
	v_pk_fma_f32 v[24:25], v[22:23], v[22:23], v[222:223] op_sel:[0,0,0] op_sel_hi:[0,1,1] neg_lo:[0,0,1]
	v_pk_mul_f32 v[222:223], v[24:25], v[22:23] op_sel:[1,1] op_sel_hi:[1,0]
	v_pk_fma_f32 v[26:27], v[24:25], v[22:23], v[222:223] op_sel:[0,0,0] op_sel_hi:[0,1,1] neg_lo:[0,0,1]
	s_waitcnt vmcnt(20)
; __device__ __forceinline__ float bf2f(u16 h){ return __uint_as_float(((unsigned)h)<<16); }
; __device__ __forceinline__ float hconv3(const u16* __restrict__ row, int t, float w0, float w1, float w2, float bias){
;   float m = bf2f(row[t]);
;   int mi=__float_as_int(m);
;   float l=__int_as_float(__builtin_amdgcn_update_dpp(0, mi, 0x138, 0xf, 0xf, false));
;   float r=__int_as_float(__builtin_amdgcn_update_dpp(0, mi, 0x130, 0xf, 0xf, false));
;   return w0*l+w1*m+w2*r+bias;
; }
; __device__ __forceinline__ void phase_hyena(KP kp_, int hf){ asm volatile("" : "+s"(kp_)); const Params p=load_params(kp_);
;     ...
;       else if (st==1){ int tq=tid; asm volatile("" : "+v"(tq));
;         _Pragma("unroll 4") for (int i=0;i<8;++i){ int t=tq+512*i;
;           float2 a0=make_float2(hconv3(rv,t,wv0,wv1,wv2,bv_), hconv3(rv+8192,t,wv0,wv1,wv2,bv_));
;           float2 a1=make_float2(hconv3(rv,t+4096,wv0,wv1,wv2,bv_), hconv3(rv+8192,t+4096,wv0,wv1,wv2,bv_));
;           fwd12_padded(Z,twA,twB,t,a0,a1); }
	v_lshlrev_b32_e32 v224, 16, v112
	v_lshlrev_b32_e32 v225, 16, v113
	v_mov_b32_e32 v226, 0
	v_mov_b32_e32 v227, 0
	v_mov_b32_e32 v80, 0
	v_mov_b32_e32 v81, 0
	v_mov_b32_dpp v226, v224 wave_shr:1 row_mask:0xf bank_mask:0xf
	v_mov_b32_dpp v227, v225 wave_shr:1 row_mask:0xf bank_mask:0xf
	v_mov_b32_dpp v80, v224 wave_shl:1 row_mask:0xf bank_mask:0xf
	v_mov_b32_dpp v81, v225 wave_shl:1 row_mask:0xf bank_mask:0xf
	v_pk_mul_f32 v[82:83], v[34:35], v[224:225]
	v_pk_fma_f32 v[82:83], v[32:33], v[226:227], v[82:83]
	v_pk_fma_f32 v[82:83], v[36:37], v[80:81], v[82:83]
	v_pk_add_f32 v[28:29], v[38:39], v[82:83]
	v_lshlrev_b32_e32 v224, 16, v114
	v_lshlrev_b32_e32 v225, 16, v115
	v_mov_b32_e32 v226, 0
	v_mov_b32_e32 v227, 0
	v_mov_b32_e32 v80, 0
	v_mov_b32_e32 v81, 0
	v_mov_b32_dpp v226, v224 wave_shr:1 row_mask:0xf bank_mask:0xf
	v_mov_b32_dpp v227, v225 wave_shr:1 row_mask:0xf bank_mask:0xf
	v_mov_b32_dpp v80, v224 wave_shl:1 row_mask:0xf bank_mask:0xf
	v_mov_b32_dpp v81, v225 wave_shl:1 row_mask:0xf bank_mask:0xf
	v_pk_mul_f32 v[82:83], v[34:35], v[224:225]
	v_pk_fma_f32 v[82:83], v[32:33], v[226:227], v[82:83]
	v_pk_fma_f32 v[82:83], v[36:37], v[80:81], v[82:83]
	v_pk_add_f32 v[30:31], v[38:39], v[82:83]
	v_pk_add_f32 v[84:85], v[28:29], v[30:31]
	ds_write_b64 v12, v[84:85] offset:8192
	v_pk_add_f32 v[74:75], v[28:29], v[30:31] op_sel:[0,1] op_sel_hi:[1,0] neg_hi:[0,1]
	v_pk_mul_f32 v[222:223], v[74:75], v[22:23] op_sel:[1,1] op_sel_hi:[1,0]
	v_pk_fma_f32 v[84:85], v[74:75], v[22:23], v[222:223] op_sel:[0,0,0] op_sel_hi:[0,1,1] neg_lo:[0,0,1]
	ds_write_b64 v12, v[84:85] offset:40960
	v_pk_add_f32 v[74:75], v[28:29], v[30:31] neg_lo:[0,1] neg_hi:[0,1]
	v_pk_mul_f32 v[222:223], v[74:75], v[24:25] op_sel:[1,1] op_sel_hi:[1,0]
	v_pk_fma_f32 v[84:85], v[74:75], v[24:25], v[222:223] op_sel:[0,0,0] op_sel_hi:[0,1,1] neg_lo:[0,0,1]
	ds_write_b64 v13, v[84:85] offset:8192
	v_pk_add_f32 v[74:75], v[28:29], v[30:31] op_sel:[0,1] op_sel_hi:[1,0] neg_lo:[0,1]
	v_pk_mul_f32 v[222:223], v[74:75], v[26:27] op_sel:[1,1] op_sel_hi:[1,0]
	v_pk_fma_f32 v[84:85], v[74:75], v[26:27], v[222:223] op_sel:[0,0,0] op_sel_hi:[0,1,1] neg_lo:[0,0,1]
	ds_write_b64 v13, v[84:85] offset:40960
	v_pk_mul_f32 v[222:223], v[64:65], v[10:11] op_sel:[1,1] op_sel_hi:[1,0]
	v_pk_fma_f32 v[22:23], v[64:65], v[10:11], v[222:223] op_sel:[0,0,0] op_sel_hi:[0,1,1] neg_lo:[0,0,1]
	v_pk_mul_f32 v[222:223], v[22:23], v[22:23] op_sel:[1,1] op_sel_hi:[1,0]
	v_pk_fma_f32 v[24:25], v[22:23], v[22:23], v[222:223] op_sel:[0,0,0] op_sel_hi:[0,1,1] neg_lo:[0,0,1]
	v_pk_mul_f32 v[222:223], v[24:25], v[22:23] op_sel:[1,1] op_sel_hi:[1,0]
	v_pk_fma_f32 v[26:27], v[24:25], v[22:23], v[222:223] op_sel:[0,0,0] op_sel_hi:[0,1,1] neg_lo:[0,0,1]
	s_waitcnt vmcnt(16)
	v_lshlrev_b32_e32 v224, 16, v116
	v_lshlrev_b32_e32 v225, 16, v117
	v_mov_b32_e32 v226, 0
	v_mov_b32_e32 v227, 0
	v_mov_b32_e32 v80, 0
	v_mov_b32_e32 v81, 0
	v_mov_b32_dpp v226, v224 wave_shr:1 row_mask:0xf bank_mask:0xf
	v_mov_b32_dpp v227, v225 wave_shr:1 row_mask:0xf bank_mask:0xf
	v_mov_b32_dpp v80, v224 wave_shl:1 row_mask:0xf bank_mask:0xf
	v_mov_b32_dpp v81, v225 wave_shl:1 row_mask:0xf bank_mask:0xf
	v_pk_mul_f32 v[82:83], v[34:35], v[224:225]
	v_pk_fma_f32 v[82:83], v[32:33], v[226:227], v[82:83]
	v_pk_fma_f32 v[82:83], v[36:37], v[80:81], v[82:83]
	v_pk_add_f32 v[28:29], v[38:39], v[82:83]
	v_lshlrev_b32_e32 v224, 16, v118
	v_lshlrev_b32_e32 v225, 16, v119
	v_mov_b32_e32 v226, 0
	v_mov_b32_e32 v227, 0
	v_mov_b32_e32 v80, 0
	v_mov_b32_e32 v81, 0
	v_mov_b32_dpp v226, v224 wave_shr:1 row_mask:0xf bank_mask:0xf
	v_mov_b32_dpp v227, v225 wave_shr:1 row_mask:0xf bank_mask:0xf
	v_mov_b32_dpp v80, v224 wave_shl:1 row_mask:0xf bank_mask:0xf
	v_mov_b32_dpp v81, v225 wave_shl:1 row_mask:0xf bank_mask:0xf
	v_pk_mul_f32 v[82:83], v[34:35], v[224:225]
	v_pk_fma_f32 v[82:83], v[32:33], v[226:227], v[82:83]
	v_pk_fma_f32 v[82:83], v[36:37], v[80:81], v[82:83]
	v_pk_add_f32 v[30:31], v[38:39], v[82:83]
	v_pk_add_f32 v[84:85], v[28:29], v[30:31]
	ds_write_b64 v12, v[84:85] offset:12288
	v_pk_add_f32 v[74:75], v[28:29], v[30:31] op_sel:[0,1] op_sel_hi:[1,0] neg_hi:[0,1]
	v_pk_mul_f32 v[222:223], v[74:75], v[22:23] op_sel:[1,1] op_sel_hi:[1,0]
	v_pk_fma_f32 v[84:85], v[74:75], v[22:23], v[222:223] op_sel:[0,0,0] op_sel_hi:[0,1,1] neg_lo:[0,0,1]
	ds_write_b64 v12, v[84:85] offset:45056
	v_pk_add_f32 v[74:75], v[28:29], v[30:31] neg_lo:[0,1] neg_hi:[0,1]
	v_pk_mul_f32 v[222:223], v[74:75], v[24:25] op_sel:[1,1] op_sel_hi:[1,0]
	v_pk_fma_f32 v[84:85], v[74:75], v[24:25], v[222:223] op_sel:[0,0,0] op_sel_hi:[0,1,1] neg_lo:[0,0,1]
	ds_write_b64 v13, v[84:85] offset:12288
	v_pk_add_f32 v[74:75], v[28:29], v[30:31] op_sel:[0,1] op_sel_hi:[1,0] neg_lo:[0,1]
	v_pk_mul_f32 v[222:223], v[74:75], v[26:27] op_sel:[1,1] op_sel_hi:[1,0]
	v_pk_fma_f32 v[84:85], v[74:75], v[26:27], v[222:223] op_sel:[0,0,0] op_sel_hi:[0,1,1] neg_lo:[0,0,1]
	ds_write_b64 v13, v[84:85] offset:45056
	v_pk_mul_f32 v[222:223], v[66:67], v[10:11] op_sel:[1,1] op_sel_hi:[1,0]
	v_pk_fma_f32 v[22:23], v[66:67], v[10:11], v[222:223] op_sel:[0,0,0] op_sel_hi:[0,1,1] neg_lo:[0,0,1]
	v_pk_mul_f32 v[222:223], v[22:23], v[22:23] op_sel:[1,1] op_sel_hi:[1,0]
	v_pk_fma_f32 v[24:25], v[22:23], v[22:23], v[222:223] op_sel:[0,0,0] op_sel_hi:[0,1,1] neg_lo:[0,0,1]
	v_pk_mul_f32 v[222:223], v[24:25], v[22:23] op_sel:[1,1] op_sel_hi:[1,0]
	v_pk_fma_f32 v[26:27], v[24:25], v[22:23], v[222:223] op_sel:[0,0,0] op_sel_hi:[0,1,1] neg_lo:[0,0,1]
	s_waitcnt vmcnt(12)
; __device__ __forceinline__ float bf2f(u16 h){ return __uint_as_float(((unsigned)h)<<16); }
; __device__ __forceinline__ float hconv3(const u16* __restrict__ row, int t, float w0, float w1, float w2, float bias){
;   float m = bf2f(row[t]);
;   int mi=__float_as_int(m);
;   float l=__int_as_float(__builtin_amdgcn_update_dpp(0, mi, 0x138, 0xf, 0xf, false));
;   float r=__int_as_float(__builtin_amdgcn_update_dpp(0, mi, 0x130, 0xf, 0xf, false));
;   return w0*l+w1*m+w2*r+bias;
; }
; __device__ __forceinline__ void phase_hyena(KP kp_, int hf){ asm volatile("" : "+s"(kp_)); const Params p=load_params(kp_);
;     ...
;       else if (st==1){ int tq=tid; asm volatile("" : "+v"(tq));
;         _Pragma("unroll 4") for (int i=0;i<8;++i){ int t=tq+512*i;
;           float2 a0=make_float2(hconv3(rv,t,wv0,wv1,wv2,bv_), hconv3(rv+8192,t,wv0,wv1,wv2,bv_));
;           float2 a1=make_float2(hconv3(rv,t+4096,wv0,wv1,wv2,bv_), hconv3(rv+8192,t+4096,wv0,wv1,wv2,bv_));
;           fwd12_padded(Z,twA,twB,t,a0,a1); }
	v_lshlrev_b32_e32 v224, 16, v120
	v_lshlrev_b32_e32 v225, 16, v121
	v_mov_b32_e32 v226, 0
	v_mov_b32_e32 v227, 0
	v_mov_b32_e32 v80, 0
	v_mov_b32_e32 v81, 0
	v_mov_b32_dpp v226, v224 wave_shr:1 row_mask:0xf bank_mask:0xf
	v_mov_b32_dpp v227, v225 wave_shr:1 row_mask:0xf bank_mask:0xf
	v_mov_b32_dpp v80, v224 wave_shl:1 row_mask:0xf bank_mask:0xf
	v_mov_b32_dpp v81, v225 wave_shl:1 row_mask:0xf bank_mask:0xf
	v_pk_mul_f32 v[82:83], v[34:35], v[224:225]
	v_pk_fma_f32 v[82:83], v[32:33], v[226:227], v[82:83]
	v_pk_fma_f32 v[82:83], v[36:37], v[80:81], v[82:83]
	v_pk_add_f32 v[28:29], v[38:39], v[82:83]
	v_lshlrev_b32_e32 v224, 16, v122
	v_lshlrev_b32_e32 v225, 16, v123
	v_mov_b32_e32 v226, 0
	v_mov_b32_e32 v227, 0
	v_mov_b32_e32 v80, 0
	v_mov_b32_e32 v81, 0
	v_mov_b32_dpp v226, v224 wave_shr:1 row_mask:0xf bank_mask:0xf
	v_mov_b32_dpp v227, v225 wave_shr:1 row_mask:0xf bank_mask:0xf
	v_mov_b32_dpp v80, v224 wave_shl:1 row_mask:0xf bank_mask:0xf
	v_mov_b32_dpp v81, v225 wave_shl:1 row_mask:0xf bank_mask:0xf
	v_pk_mul_f32 v[82:83], v[34:35], v[224:225]
	v_pk_fma_f32 v[82:83], v[32:33], v[226:227], v[82:83]
	v_pk_fma_f32 v[82:83], v[36:37], v[80:81], v[82:83]
	v_pk_add_f32 v[30:31], v[38:39], v[82:83]
	v_pk_add_f32 v[84:85], v[28:29], v[30:31]
	ds_write_b64 v12, v[84:85] offset:16384
	v_pk_add_f32 v[74:75], v[28:29], v[30:31] op_sel:[0,1] op_sel_hi:[1,0] neg_hi:[0,1]
	v_pk_mul_f32 v[222:223], v[74:75], v[22:23] op_sel:[1,1] op_sel_hi:[1,0]
	v_pk_fma_f32 v[84:85], v[74:75], v[22:23], v[222:223] op_sel:[0,0,0] op_sel_hi:[0,1,1] neg_lo:[0,0,1]
	ds_write_b64 v12, v[84:85] offset:49152
	v_pk_add_f32 v[74:75], v[28:29], v[30:31] neg_lo:[0,1] neg_hi:[0,1]
	v_pk_mul_f32 v[222:223], v[74:75], v[24:25] op_sel:[1,1] op_sel_hi:[1,0]
	v_pk_fma_f32 v[84:85], v[74:75], v[24:25], v[222:223] op_sel:[0,0,0] op_sel_hi:[0,1,1] neg_lo:[0,0,1]
	ds_write_b64 v13, v[84:85] offset:16384
	v_pk_add_f32 v[74:75], v[28:29], v[30:31] op_sel:[0,1] op_sel_hi:[1,0] neg_lo:[0,1]
	v_pk_mul_f32 v[222:223], v[74:75], v[26:27] op_sel:[1,1] op_sel_hi:[1,0]
	v_pk_fma_f32 v[84:85], v[74:75], v[26:27], v[222:223] op_sel:[0,0,0] op_sel_hi:[0,1,1] neg_lo:[0,0,1]
	ds_write_b64 v13, v[84:85] offset:49152
	v_pk_mul_f32 v[222:223], v[68:69], v[10:11] op_sel:[1,1] op_sel_hi:[1,0]
	v_pk_fma_f32 v[22:23], v[68:69], v[10:11], v[222:223] op_sel:[0,0,0] op_sel_hi:[0,1,1] neg_lo:[0,0,1]
	v_pk_mul_f32 v[222:223], v[22:23], v[22:23] op_sel:[1,1] op_sel_hi:[1,0]
	v_pk_fma_f32 v[24:25], v[22:23], v[22:23], v[222:223] op_sel:[0,0,0] op_sel_hi:[0,1,1] neg_lo:[0,0,1]
	v_pk_mul_f32 v[222:223], v[24:25], v[22:23] op_sel:[1,1] op_sel_hi:[1,0]
	v_pk_fma_f32 v[26:27], v[24:25], v[22:23], v[222:223] op_sel:[0,0,0] op_sel_hi:[0,1,1] neg_lo:[0,0,1]
	s_waitcnt vmcnt(8)
	v_lshlrev_b32_e32 v224, 16, v124
	v_lshlrev_b32_e32 v225, 16, v125
	v_mov_b32_e32 v226, 0
	v_mov_b32_e32 v227, 0
	v_mov_b32_e32 v80, 0
	v_mov_b32_e32 v81, 0
	v_mov_b32_dpp v226, v224 wave_shr:1 row_mask:0xf bank_mask:0xf
	v_mov_b32_dpp v227, v225 wave_shr:1 row_mask:0xf bank_mask:0xf
	v_mov_b32_dpp v80, v224 wave_shl:1 row_mask:0xf bank_mask:0xf
	v_mov_b32_dpp v81, v225 wave_shl:1 row_mask:0xf bank_mask:0xf
	v_pk_mul_f32 v[82:83], v[34:35], v[224:225]
	v_pk_fma_f32 v[82:83], v[32:33], v[226:227], v[82:83]
	v_pk_fma_f32 v[82:83], v[36:37], v[80:81], v[82:83]
	v_pk_add_f32 v[28:29], v[38:39], v[82:83]
	v_lshlrev_b32_e32 v224, 16, v126
	v_lshlrev_b32_e32 v225, 16, v127
	v_mov_b32_e32 v226, 0
	v_mov_b32_e32 v227, 0
	v_mov_b32_e32 v80, 0
	v_mov_b32_e32 v81, 0
	v_mov_b32_dpp v226, v224 wave_shr:1 row_mask:0xf bank_mask:0xf
	v_mov_b32_dpp v227, v225 wave_shr:1 row_mask:0xf bank_mask:0xf
	v_mov_b32_dpp v80, v224 wave_shl:1 row_mask:0xf bank_mask:0xf
	v_mov_b32_dpp v81, v225 wave_shl:1 row_mask:0xf bank_mask:0xf
	v_pk_mul_f32 v[82:83], v[34:35], v[224:225]
	v_pk_fma_f32 v[82:83], v[32:33], v[226:227], v[82:83]
	v_pk_fma_f32 v[82:83], v[36:37], v[80:81], v[82:83]
	v_pk_add_f32 v[30:31], v[38:39], v[82:83]
	v_pk_add_f32 v[84:85], v[28:29], v[30:31]
	ds_write_b64 v12, v[84:85] offset:20480
	v_pk_add_f32 v[74:75], v[28:29], v[30:31] op_sel:[0,1] op_sel_hi:[1,0] neg_hi:[0,1]
	v_pk_mul_f32 v[222:223], v[74:75], v[22:23] op_sel:[1,1] op_sel_hi:[1,0]
	v_pk_fma_f32 v[84:85], v[74:75], v[22:23], v[222:223] op_sel:[0,0,0] op_sel_hi:[0,1,1] neg_lo:[0,0,1]
	ds_write_b64 v12, v[84:85] offset:53248
	v_pk_add_f32 v[74:75], v[28:29], v[30:31] neg_lo:[0,1] neg_hi:[0,1]
	v_pk_mul_f32 v[222:223], v[74:75], v[24:25] op_sel:[1,1] op_sel_hi:[1,0]
	v_pk_fma_f32 v[84:85], v[74:75], v[24:25], v[222:223] op_sel:[0,0,0] op_sel_hi:[0,1,1] neg_lo:[0,0,1]
	ds_write_b64 v13, v[84:85] offset:20480
	v_pk_add_f32 v[74:75], v[28:29], v[30:31] op_sel:[0,1] op_sel_hi:[1,0] neg_lo:[0,1]
	v_pk_mul_f32 v[222:223], v[74:75], v[26:27] op_sel:[1,1] op_sel_hi:[1,0]
	v_pk_fma_f32 v[84:85], v[74:75], v[26:27], v[222:223] op_sel:[0,0,0] op_sel_hi:[0,1,1] neg_lo:[0,0,1]
	ds_write_b64 v13, v[84:85] offset:53248
	v_pk_mul_f32 v[222:223], v[70:71], v[10:11] op_sel:[1,1] op_sel_hi:[1,0]
	v_pk_fma_f32 v[22:23], v[70:71], v[10:11], v[222:223] op_sel:[0,0,0] op_sel_hi:[0,1,1] neg_lo:[0,0,1]
	v_pk_mul_f32 v[222:223], v[22:23], v[22:23] op_sel:[1,1] op_sel_hi:[1,0]
	v_pk_fma_f32 v[24:25], v[22:23], v[22:23], v[222:223] op_sel:[0,0,0] op_sel_hi:[0,1,1] neg_lo:[0,0,1]
	v_pk_mul_f32 v[222:223], v[24:25], v[22:23] op_sel:[1,1] op_sel_hi:[1,0]
	v_pk_fma_f32 v[26:27], v[24:25], v[22:23], v[222:223] op_sel:[0,0,0] op_sel_hi:[0,1,1] neg_lo:[0,0,1]
	s_waitcnt vmcnt(4)
; __device__ __forceinline__ float bf2f(u16 h){ return __uint_as_float(((unsigned)h)<<16); }
; __device__ __forceinline__ float hconv3(const u16* __restrict__ row, int t, float w0, float w1, float w2, float bias){
;   float m = bf2f(row[t]);
;   int mi=__float_as_int(m);
;   float l=__int_as_float(__builtin_amdgcn_update_dpp(0, mi, 0x138, 0xf, 0xf, false));
;   float r=__int_as_float(__builtin_amdgcn_update_dpp(0, mi, 0x130, 0xf, 0xf, false));
;   return w0*l+w1*m+w2*r+bias;
; }
; __device__ __forceinline__ void phase_hyena(KP kp_, int hf){ asm volatile("" : "+s"(kp_)); const Params p=load_params(kp_);
;     ...
;       else if (st==1){ int tq=tid; asm volatile("" : "+v"(tq));
;         _Pragma("unroll 4") for (int i=0;i<8;++i){ int t=tq+512*i;
;           float2 a0=make_float2(hconv3(rv,t,wv0,wv1,wv2,bv_), hconv3(rv+8192,t,wv0,wv1,wv2,bv_));
;           float2 a1=make_float2(hconv3(rv,t+4096,wv0,wv1,wv2,bv_), hconv3(rv+8192,t+4096,wv0,wv1,wv2,bv_));
;           fwd12_padded(Z,twA,twB,t,a0,a1); }
;         __syncthreads();
	v_lshlrev_b32_e32 v224, 16, v134
	v_lshlrev_b32_e32 v225, 16, v135
	v_mov_b32_e32 v226, 0
	v_mov_b32_e32 v227, 0
	v_mov_b32_e32 v80, 0
	v_mov_b32_e32 v81, 0
	v_mov_b32_dpp v226, v224 wave_shr:1 row_mask:0xf bank_mask:0xf
	v_mov_b32_dpp v227, v225 wave_shr:1 row_mask:0xf bank_mask:0xf
	v_mov_b32_dpp v80, v224 wave_shl:1 row_mask:0xf bank_mask:0xf
	v_mov_b32_dpp v81, v225 wave_shl:1 row_mask:0xf bank_mask:0xf
	v_pk_mul_f32 v[82:83], v[34:35], v[224:225]
	v_pk_fma_f32 v[82:83], v[32:33], v[226:227], v[82:83]
	v_pk_fma_f32 v[82:83], v[36:37], v[80:81], v[82:83]
	v_pk_add_f32 v[28:29], v[38:39], v[82:83]
	v_lshlrev_b32_e32 v224, 16, v136
	v_lshlrev_b32_e32 v225, 16, v137
	v_mov_b32_e32 v226, 0
	v_mov_b32_e32 v227, 0
	v_mov_b32_e32 v80, 0
	v_mov_b32_e32 v81, 0
	v_mov_b32_dpp v226, v224 wave_shr:1 row_mask:0xf bank_mask:0xf
	v_mov_b32_dpp v227, v225 wave_shr:1 row_mask:0xf bank_mask:0xf
	v_mov_b32_dpp v80, v224 wave_shl:1 row_mask:0xf bank_mask:0xf
	v_mov_b32_dpp v81, v225 wave_shl:1 row_mask:0xf bank_mask:0xf
	v_pk_mul_f32 v[82:83], v[34:35], v[224:225]
	v_pk_fma_f32 v[82:83], v[32:33], v[226:227], v[82:83]
	v_pk_fma_f32 v[82:83], v[36:37], v[80:81], v[82:83]
	v_pk_add_f32 v[30:31], v[38:39], v[82:83]
	v_pk_add_f32 v[84:85], v[28:29], v[30:31]
	ds_write_b64 v12, v[84:85] offset:24576
	v_pk_add_f32 v[74:75], v[28:29], v[30:31] op_sel:[0,1] op_sel_hi:[1,0] neg_hi:[0,1]
	v_pk_mul_f32 v[222:223], v[74:75], v[22:23] op_sel:[1,1] op_sel_hi:[1,0]
	v_pk_fma_f32 v[84:85], v[74:75], v[22:23], v[222:223] op_sel:[0,0,0] op_sel_hi:[0,1,1] neg_lo:[0,0,1]
	ds_write_b64 v12, v[84:85] offset:57344
	v_pk_add_f32 v[74:75], v[28:29], v[30:31] neg_lo:[0,1] neg_hi:[0,1]
	v_pk_mul_f32 v[222:223], v[74:75], v[24:25] op_sel:[1,1] op_sel_hi:[1,0]
	v_pk_fma_f32 v[84:85], v[74:75], v[24:25], v[222:223] op_sel:[0,0,0] op_sel_hi:[0,1,1] neg_lo:[0,0,1]
	ds_write_b64 v13, v[84:85] offset:24576
	v_pk_add_f32 v[74:75], v[28:29], v[30:31] op_sel:[0,1] op_sel_hi:[1,0] neg_lo:[0,1]
	v_pk_mul_f32 v[222:223], v[74:75], v[26:27] op_sel:[1,1] op_sel_hi:[1,0]
	v_pk_fma_f32 v[84:85], v[74:75], v[26:27], v[222:223] op_sel:[0,0,0] op_sel_hi:[0,1,1] neg_lo:[0,0,1]
	ds_write_b64 v13, v[84:85] offset:57344
	v_pk_mul_f32 v[222:223], v[72:73], v[10:11] op_sel:[1,1] op_sel_hi:[1,0]
	v_pk_fma_f32 v[22:23], v[72:73], v[10:11], v[222:223] op_sel:[0,0,0] op_sel_hi:[0,1,1] neg_lo:[0,0,1]
	v_pk_mul_f32 v[222:223], v[22:23], v[22:23] op_sel:[1,1] op_sel_hi:[1,0]
	v_pk_fma_f32 v[24:25], v[22:23], v[22:23], v[222:223] op_sel:[0,0,0] op_sel_hi:[0,1,1] neg_lo:[0,0,1]
	v_pk_mul_f32 v[222:223], v[24:25], v[22:23] op_sel:[1,1] op_sel_hi:[1,0]
	v_pk_fma_f32 v[26:27], v[24:25], v[22:23], v[222:223] op_sel:[0,0,0] op_sel_hi:[0,1,1] neg_lo:[0,0,1]
	s_waitcnt vmcnt(0)
	v_lshlrev_b32_e32 v224, 16, v138
	v_lshlrev_b32_e32 v225, 16, v139
	v_mov_b32_e32 v226, 0
	v_mov_b32_e32 v227, 0
	v_mov_b32_e32 v80, 0
	v_mov_b32_e32 v81, 0
	v_mov_b32_dpp v226, v224 wave_shr:1 row_mask:0xf bank_mask:0xf
	v_mov_b32_dpp v227, v225 wave_shr:1 row_mask:0xf bank_mask:0xf
	v_mov_b32_dpp v80, v224 wave_shl:1 row_mask:0xf bank_mask:0xf
	v_mov_b32_dpp v81, v225 wave_shl:1 row_mask:0xf bank_mask:0xf
	v_pk_mul_f32 v[82:83], v[34:35], v[224:225]
	v_pk_fma_f32 v[82:83], v[32:33], v[226:227], v[82:83]
	v_pk_fma_f32 v[82:83], v[36:37], v[80:81], v[82:83]
	v_pk_add_f32 v[28:29], v[38:39], v[82:83]
	v_lshlrev_b32_e32 v224, 16, v140
	v_lshlrev_b32_e32 v225, 16, v141
	v_mov_b32_e32 v226, 0
	v_mov_b32_e32 v227, 0
	v_mov_b32_e32 v80, 0
	v_mov_b32_e32 v81, 0
	v_mov_b32_dpp v226, v224 wave_shr:1 row_mask:0xf bank_mask:0xf
	v_mov_b32_dpp v227, v225 wave_shr:1 row_mask:0xf bank_mask:0xf
	v_mov_b32_dpp v80, v224 wave_shl:1 row_mask:0xf bank_mask:0xf
	v_mov_b32_dpp v81, v225 wave_shl:1 row_mask:0xf bank_mask:0xf
	v_pk_mul_f32 v[82:83], v[34:35], v[224:225]
	v_pk_fma_f32 v[82:83], v[32:33], v[226:227], v[82:83]
	v_pk_fma_f32 v[82:83], v[36:37], v[80:81], v[82:83]
	v_pk_add_f32 v[30:31], v[38:39], v[82:83]
	v_pk_add_f32 v[84:85], v[28:29], v[30:31]
	ds_write_b64 v12, v[84:85] offset:28672
	v_pk_add_f32 v[74:75], v[28:29], v[30:31] op_sel:[0,1] op_sel_hi:[1,0] neg_hi:[0,1]
	v_pk_mul_f32 v[222:223], v[74:75], v[22:23] op_sel:[1,1] op_sel_hi:[1,0]
	v_pk_fma_f32 v[84:85], v[74:75], v[22:23], v[222:223] op_sel:[0,0,0] op_sel_hi:[0,1,1] neg_lo:[0,0,1]
	ds_write_b64 v12, v[84:85] offset:61440
	v_pk_add_f32 v[74:75], v[28:29], v[30:31] neg_lo:[0,1] neg_hi:[0,1]
	v_pk_mul_f32 v[222:223], v[74:75], v[24:25] op_sel:[1,1] op_sel_hi:[1,0]
	v_pk_fma_f32 v[84:85], v[74:75], v[24:25], v[222:223] op_sel:[0,0,0] op_sel_hi:[0,1,1] neg_lo:[0,0,1]
	ds_write_b64 v13, v[84:85] offset:28672
	v_pk_add_f32 v[74:75], v[28:29], v[30:31] op_sel:[0,1] op_sel_hi:[1,0] neg_lo:[0,1]
	v_pk_mul_f32 v[222:223], v[74:75], v[26:27] op_sel:[1,1] op_sel_hi:[1,0]
	v_pk_fma_f32 v[84:85], v[74:75], v[26:27], v[222:223] op_sel:[0,0,0] op_sel_hi:[0,1,1] neg_lo:[0,0,1]
	ds_write_b64 v13, v[84:85] offset:61440
	s_mov_b32 s50, 0x2000
	s_mov_b32 s51, 0
	s_waitcnt lgkmcnt(0)
	s_barrier
